# v52 + P10 GLU epilogue: all 8 z-row loads issued at the epilogue start into dead K-loop fragment regs, per-chunk wait vmcnt(7) instead of load-right-before-use + vmcnt(0)
# baseline (speedup 1.0000x reference)
; __device__ __forceinline__ unsigned pk2(float lo, float hi) { f32x2 v = {lo, hi}; nbf2 r = __builtin_convertvector(v, nbf2); return __builtin_bit_cast(unsigned, r); }
; __device__ __forceinline__ float bf_lo(unsigned w) { return __uint_as_float(w << 16); }
; __device__ __forceinline__ float bf_hi(unsigned w) { return __uint_as_float(w & 0xffff0000u); }
; __device__ __forceinline__ float silu_f(float z) { return z * fast_rcp(1.0f + fast_exp2(-z * LOG2E)); }
; __device__ __forceinline__ float sigmoid_f(float z) { return fast_rcp(1.0f + fast_exp2(-z * LOG2E)); }
;     __device__ __forceinline__ void operator()(f32x4 (&acc)[2][2][4][2], const pg8::Unit& u, int wr, int wc, int fr, int fq, LAS unsigned char* lds) const {
;     ...
;                 const int r = u.pm * 256 + ai * 128 + wr * 64 + m * 16 + fr;
;                 const int oc = u.pn * 128 + wc * 32 + 8 * fq;
;                 const u32x4 zw = *(const u32x4*)(UZ + (size_t)r * NUZ + 1024 + oc);
;                 const f32x4 a0 = acc[ai][0][m][0], a1 = acc[ai][0][m][1], g0 = acc[ai][1][m][0], g1 = acc[ai][1][m][1];
;                 float o[8];
;                 o[0] = a0[0] * sigmoid_f(g0[0]) * silu_f(bf_lo(zw.x)); o[1] = a0[1] * sigmoid_f(g0[1]) * silu_f(bf_hi(zw.x));
;                 o[2] = a0[2] * sigmoid_f(g0[2]) * silu_f(bf_lo(zw.y)); o[3] = a0[3] * sigmoid_f(g0[3]) * silu_f(bf_hi(zw.y));
;                 o[4] = a1[0] * sigmoid_f(g1[0]) * silu_f(bf_lo(zw.z)); o[5] = a1[1] * sigmoid_f(g1[1]) * silu_f(bf_hi(zw.z));
;                 o[6] = a1[2] * sigmoid_f(g1[2]) * silu_f(bf_lo(zw.w)); o[7] = a1[3] * sigmoid_f(g1[3]) * silu_f(bf_hi(zw.w));
;                 u32x4 w; w.x = pk2(o[0], o[1]); w.y = pk2(o[2], o[3]); w.z = pk2(o[4], o[5]); w.w = pk2(o[6], o[7]);
;                 *(u32x4*)(O + (size_t)r * D + oc) = w;
.LBB0_837:
	v_lshl_add_u32 v146, s40, 8, v148
	v_lshl_or_b32 v144, s62, 7, v150
	v_ashrrev_i32_e32 v147, 31, v146
	v_ashrrev_i32_e32 v145, 31, v144
	v_lshlrev_b64 v[154:155], 12, v[146:147]
	v_lshl_add_u64 v[154:155], s[18:19], 0, v[154:155]
	v_lshlrev_b64 v[144:145], 1, v[144:145]
	v_lshl_add_u64 v[154:155], v[154:155], 0, v[144:145]
	s_mov_b32 s96, 0x10000
	s_mov_b32 s97, 0
	s_mov_b32 s98, 0x80000
	s_mov_b32 s99, 0
	v_lshl_add_u64 v[228:229], v[154:155], 0, s[96:97]
	v_lshl_add_u64 v[230:231], v[228:229], 0, s[96:97]
	v_lshl_add_u64 v[232:233], v[230:231], 0, s[96:97]
	v_lshl_add_u64 v[234:235], v[154:155], 0, s[98:99]
	v_lshl_add_u64 v[236:237], v[234:235], 0, s[96:97]
	v_lshl_add_u64 v[238:239], v[236:237], 0, s[96:97]
	v_lshl_add_u64 v[240:241], v[238:239], 0, s[96:97]
	global_load_dwordx4 v[194:197], v[154:155], off offset:2048
	global_load_dwordx4 v[198:201], v[228:229], off offset:2048
	global_load_dwordx4 v[202:205], v[230:231], off offset:2048
	global_load_dwordx4 v[206:209], v[232:233], off offset:2048
	global_load_dwordx4 v[210:213], v[234:235], off offset:2048
	global_load_dwordx4 v[214:217], v[236:237], off offset:2048
	global_load_dwordx4 v[218:221], v[238:239], off offset:2048
	global_load_dwordx4 v[222:225], v[240:241], off offset:2048
	v_mul_f32_e32 v124, 0xbfb8aa3b, v124
	v_mul_f32_e32 v125, 0xbfb8aa3b, v125
	v_mul_f32_e32 v126, 0xbfb8aa3b, v126
	v_mul_f32_e32 v127, 0xbfb8aa3b, v127
	v_mul_f32_e32 v120, 0xbfb8aa3b, v120
	v_mul_f32_e32 v121, 0xbfb8aa3b, v121
	v_mul_f32_e32 v122, 0xbfb8aa3b, v122
	v_mul_f32_e32 v123, 0xbfb8aa3b, v123
	v_exp_f32_e32 v124, v124
	v_exp_f32_e32 v125, v125
	v_exp_f32_e32 v126, v126
	v_exp_f32_e32 v127, v127
	v_exp_f32_e32 v158, v120
	v_exp_f32_e32 v159, v121
	v_exp_f32_e32 v122, v122
	v_exp_f32_e32 v123, v123
	v_lshlrev_b64 v[120:121], 11, v[146:147]
	v_add_f32_e32 v124, 1.0, v124
	v_add_f32_e32 v125, 1.0, v125
	v_add_f32_e32 v126, 1.0, v126
	v_add_f32_e32 v127, 1.0, v127
	v_add_f32_e32 v147, 1.0, v158
	v_add_f32_e32 v158, 1.0, v159
	v_add_f32_e32 v159, 1.0, v122
	v_add_f32_e32 v160, 1.0, v123
	v_rcp_f32_e32 v122, v124
	v_rcp_f32_e32 v123, v125
	v_rcp_f32_e32 v124, v126
	v_rcp_f32_e32 v125, v127
	v_rcp_f32_e32 v126, v147
	v_rcp_f32_e32 v127, v158
	v_rcp_f32_e32 v158, v159
	v_rcp_f32_e32 v159, v160
	v_pk_mul_f32 v[116:117], v[116:117], v[122:123]
	v_pk_mul_f32 v[118:119], v[118:119], v[124:125]
	v_pk_mul_f32 v[112:113], v[112:113], v[126:127]
	v_pk_mul_f32 v[114:115], v[114:115], v[158:159]
	v_lshl_add_u64 v[120:121], s[16:17], 0, v[120:121]
	v_mul_f32_e32 v108, 0xbfb8aa3b, v108
	v_mul_f32_e32 v109, 0xbfb8aa3b, v109
	v_mul_f32_e32 v110, 0xbfb8aa3b, v110
	v_mul_f32_e32 v111, 0xbfb8aa3b, v111
	v_mul_f32_e32 v100, 0xbfb8aa3b, v100
	v_mul_f32_e32 v101, 0xbfb8aa3b, v101
	v_exp_f32_e32 v108, v108
	v_exp_f32_e32 v109, v109
	v_mul_f32_e32 v102, 0xbfb8aa3b, v102
	v_mul_f32_e32 v103, 0xbfb8aa3b, v103
	v_exp_f32_e32 v110, v110
	v_exp_f32_e32 v111, v111
	v_exp_f32_e32 v100, v100
	v_exp_f32_e32 v101, v101
	v_exp_f32_e32 v102, v102
	v_exp_f32_e32 v103, v103
	v_add_f32_e32 v108, 1.0, v108
	v_add_f32_e32 v109, 1.0, v109
	v_add_f32_e32 v110, 1.0, v110
	v_add_f32_e32 v111, 1.0, v111
	v_mul_f32_e32 v92, 0xbfb8aa3b, v92
	v_mul_f32_e32 v93, 0xbfb8aa3b, v93
	v_mul_f32_e32 v94, 0xbfb8aa3b, v94
	v_mul_f32_e32 v95, 0xbfb8aa3b, v95
	v_mul_f32_e32 v84, 0xbfb8aa3b, v84
	v_mul_f32_e32 v85, 0xbfb8aa3b, v85
	v_exp_f32_e32 v92, v92
	v_exp_f32_e32 v93, v93
	v_mul_f32_e32 v86, 0xbfb8aa3b, v86
	v_mul_f32_e32 v87, 0xbfb8aa3b, v87
	v_exp_f32_e32 v94, v94
	v_exp_f32_e32 v95, v95
	v_exp_f32_e32 v84, v84
	v_exp_f32_e32 v85, v85
	v_exp_f32_e32 v86, v86
	v_exp_f32_e32 v87, v87
	v_add_f32_e32 v92, 1.0, v92
	v_add_f32_e32 v93, 1.0, v93
	v_add_f32_e32 v94, 1.0, v94
	v_add_f32_e32 v95, 1.0, v95
	v_mul_f32_e32 v76, 0xbfb8aa3b, v76
	s_waitcnt vmcnt(7)
	v_lshlrev_b32_e32 v122, 16, v194
	v_and_b32_e32 v123, 0xffff0000, v194
	v_lshlrev_b32_e32 v124, 16, v195
	v_and_b32_e32 v125, 0xffff0000, v195
	v_lshlrev_b32_e32 v126, 16, v196
	v_and_b32_e32 v127, 0xffff0000, v196
	v_lshlrev_b32_e32 v154, 16, v197
	v_and_b32_e32 v155, 0xffff0000, v197
	v_mul_f32_e32 v147, 0xbfb8aa3b, v122
	v_mul_f32_e32 v156, 0xbfb8aa3b, v123
	v_mul_f32_e32 v157, 0xbfb8aa3b, v124
	v_mul_f32_e32 v158, 0xbfb8aa3b, v125
	v_mul_f32_e32 v159, 0xbfb8aa3b, v126
	v_mul_f32_e32 v160, 0xbfb8aa3b, v127
	v_mul_f32_e32 v161, 0xbfb8aa3b, v154
	v_mul_f32_e32 v162, 0xbfb8aa3b, v155
	v_exp_f32_e32 v147, v147
	v_exp_f32_e32 v156, v156
	v_exp_f32_e32 v157, v157
	v_exp_f32_e32 v158, v158
	v_exp_f32_e32 v159, v159
	v_exp_f32_e32 v160, v160
	v_exp_f32_e32 v161, v161
	v_exp_f32_e32 v162, v162
	v_add_f32_e32 v147, 1.0, v147
	v_add_f32_e32 v163, 1.0, v156
	v_add_f32_e32 v164, 1.0, v157
	v_add_f32_e32 v165, 1.0, v158
	v_add_f32_e32 v166, 1.0, v159
	v_add_f32_e32 v167, 1.0, v160
	v_add_f32_e32 v168, 1.0, v161
	v_add_f32_e32 v169, 1.0, v162
	v_rcp_f32_e32 v156, v147
	v_rcp_f32_e32 v157, v163
	v_rcp_f32_e32 v158, v164
	v_rcp_f32_e32 v159, v165
	v_rcp_f32_e32 v160, v166
	v_rcp_f32_e32 v161, v167
	v_rcp_f32_e32 v162, v168
	v_rcp_f32_e32 v163, v169
	v_pk_mul_f32 v[122:123], v[156:157], v[122:123]
	v_pk_mul_f32 v[124:125], v[158:159], v[124:125]
	v_pk_mul_f32 v[126:127], v[160:161], v[126:127]
	v_pk_mul_f32 v[154:155], v[162:163], v[154:155]
	v_pk_mul_f32 v[116:117], v[116:117], v[122:123]
	v_pk_mul_f32 v[118:119], v[118:119], v[124:125]
	v_pk_mul_f32 v[122:123], v[112:113], v[126:127]
	v_pk_mul_f32 v[124:125], v[114:115], v[154:155]
	v_cvt_pk_bf16_f32 v112, v116, v117
	v_cvt_pk_bf16_f32 v113, v118, v119
	v_cvt_pk_bf16_f32 v114, v122, v123
	v_cvt_pk_bf16_f32 v115, v124, v125
	v_lshl_add_u64 v[116:117], v[120:121], 0, v[144:145]
; __device__ __forceinline__ unsigned pk2(float lo, float hi) { f32x2 v = {lo, hi}; nbf2 r = __builtin_convertvector(v, nbf2); return __builtin_bit_cast(unsigned, r); }
; __device__ __forceinline__ float bf_lo(unsigned w) { return __uint_as_float(w << 16); }
; __device__ __forceinline__ float bf_hi(unsigned w) { return __uint_as_float(w & 0xffff0000u); }
; __device__ __forceinline__ float silu_f(float z) { return z * fast_rcp(1.0f + fast_exp2(-z * LOG2E)); }
; __device__ __forceinline__ float sigmoid_f(float z) { return fast_rcp(1.0f + fast_exp2(-z * LOG2E)); }
;     __device__ __forceinline__ void operator()(f32x4 (&acc)[2][2][4][2], const pg8::Unit& u, int wr, int wc, int fr, int fq, LAS unsigned char* lds) const {
;     ...
;                 const int r = u.pm * 256 + ai * 128 + wr * 64 + m * 16 + fr;
;                 const int oc = u.pn * 128 + wc * 32 + 8 * fq;
;                 const u32x4 zw = *(const u32x4*)(UZ + (size_t)r * NUZ + 1024 + oc);
;                 const f32x4 a0 = acc[ai][0][m][0], a1 = acc[ai][0][m][1], g0 = acc[ai][1][m][0], g1 = acc[ai][1][m][1];
;                 float o[8];
;                 o[0] = a0[0] * sigmoid_f(g0[0]) * silu_f(bf_lo(zw.x)); o[1] = a0[1] * sigmoid_f(g0[1]) * silu_f(bf_hi(zw.x));
;                 o[2] = a0[2] * sigmoid_f(g0[2]) * silu_f(bf_lo(zw.y)); o[3] = a0[3] * sigmoid_f(g0[3]) * silu_f(bf_hi(zw.y));
;                 o[4] = a1[0] * sigmoid_f(g1[0]) * silu_f(bf_lo(zw.z)); o[5] = a1[1] * sigmoid_f(g1[1]) * silu_f(bf_hi(zw.z));
;                 o[6] = a1[2] * sigmoid_f(g1[2]) * silu_f(bf_lo(zw.w)); o[7] = a1[3] * sigmoid_f(g1[3]) * silu_f(bf_hi(zw.w));
;                 u32x4 w; w.x = pk2(o[0], o[1]); w.y = pk2(o[2], o[3]); w.z = pk2(o[4], o[5]); w.w = pk2(o[6], o[7]);
;                 *(u32x4*)(O + (size_t)r * D + oc) = w;
	global_store_dwordx4 v[116:117], v[112:115], off
	v_or_b32_e32 v116, 16, v146
	v_ashrrev_i32_e32 v117, 31, v116
	v_add_f32_e32 v118, 1.0, v100
	v_add_f32_e32 v119, 1.0, v101
	v_rcp_f32_e32 v100, v108
	v_rcp_f32_e32 v101, v109
	v_add_f32_e32 v120, 1.0, v102
	v_add_f32_e32 v121, 1.0, v103
	v_rcp_f32_e32 v102, v110
	v_rcp_f32_e32 v103, v111
	v_rcp_f32_e32 v108, v118
	v_rcp_f32_e32 v109, v119
	v_rcp_f32_e32 v110, v120
	v_rcp_f32_e32 v111, v121
	v_pk_mul_f32 v[100:101], v[104:105], v[100:101]
	v_pk_mul_f32 v[102:103], v[106:107], v[102:103]
	v_pk_mul_f32 v[96:97], v[96:97], v[108:109]
	v_pk_mul_f32 v[98:99], v[98:99], v[110:111]
	v_mul_f32_e32 v77, 0xbfb8aa3b, v77
	v_mul_f32_e32 v68, 0xbfb8aa3b, v68
	v_mul_f32_e32 v69, 0xbfb8aa3b, v69
	v_mul_f32_e32 v78, 0xbfb8aa3b, v78
	v_mul_f32_e32 v79, 0xbfb8aa3b, v79
	v_exp_f32_e32 v76, v76
	v_exp_f32_e32 v77, v77
	v_exp_f32_e32 v68, v68
	v_exp_f32_e32 v69, v69
	v_mul_f32_e32 v70, 0xbfb8aa3b, v70
	v_mul_f32_e32 v71, 0xbfb8aa3b, v71
	v_exp_f32_e32 v78, v78
	v_exp_f32_e32 v79, v79
	v_exp_f32_e32 v70, v70
	v_exp_f32_e32 v71, v71
	v_add_f32_e32 v76, 1.0, v76
	v_add_f32_e32 v77, 1.0, v77
	v_add_f32_e32 v78, 1.0, v78
	v_add_f32_e32 v79, 1.0, v79
	v_mul_f32_e32 v60, 0xbfb8aa3b, v60
	v_mul_f32_e32 v61, 0xbfb8aa3b, v61
	v_mul_f32_e32 v62, 0xbfb8aa3b, v62
	v_mul_f32_e32 v63, 0xbfb8aa3b, v63
	v_mul_f32_e32 v52, 0xbfb8aa3b, v52
	v_mul_f32_e32 v53, 0xbfb8aa3b, v53
	v_exp_f32_e32 v60, v60
	v_exp_f32_e32 v61, v61
	v_mul_f32_e32 v54, 0xbfb8aa3b, v54
	v_mul_f32_e32 v55, 0xbfb8aa3b, v55
	v_exp_f32_e32 v62, v62
	v_exp_f32_e32 v63, v63
	v_exp_f32_e32 v52, v52
	v_exp_f32_e32 v53, v53
	v_exp_f32_e32 v54, v54
	v_exp_f32_e32 v55, v55
	v_add_f32_e32 v60, 1.0, v60
	v_add_f32_e32 v61, 1.0, v61
	v_add_f32_e32 v62, 1.0, v62
	v_add_f32_e32 v63, 1.0, v63
	v_mul_f32_e32 v44, 0xbfb8aa3b, v44
	v_mul_f32_e32 v45, 0xbfb8aa3b, v45
	v_mul_f32_e32 v46, 0xbfb8aa3b, v46
	v_mul_f32_e32 v47, 0xbfb8aa3b, v47
	v_mul_f32_e32 v36, 0xbfb8aa3b, v36
	v_mul_f32_e32 v37, 0xbfb8aa3b, v37
	v_exp_f32_e32 v44, v44
	v_exp_f32_e32 v45, v45
	v_mul_f32_e32 v38, 0xbfb8aa3b, v38
	v_mul_f32_e32 v39, 0xbfb8aa3b, v39
	v_exp_f32_e32 v46, v46
	v_exp_f32_e32 v47, v47
	v_exp_f32_e32 v36, v36
	v_exp_f32_e32 v37, v37
	v_exp_f32_e32 v38, v38
	v_exp_f32_e32 v39, v39
	v_add_f32_e32 v44, 1.0, v44
	v_add_f32_e32 v45, 1.0, v45
	v_add_f32_e32 v46, 1.0, v46
	v_add_f32_e32 v47, 1.0, v47
	v_mul_f32_e32 v28, 0xbfb8aa3b, v28
	v_mul_f32_e32 v29, 0xbfb8aa3b, v29
	v_mul_f32_e32 v30, 0xbfb8aa3b, v30
	v_mul_f32_e32 v31, 0xbfb8aa3b, v31
	s_waitcnt vmcnt(7)
	v_lshlrev_b32_e32 v104, 16, v198
	v_and_b32_e32 v105, 0xffff0000, v198
	v_lshlrev_b32_e32 v106, 16, v199
	v_and_b32_e32 v107, 0xffff0000, v199
	v_lshlrev_b32_e32 v108, 16, v200
	v_and_b32_e32 v109, 0xffff0000, v200
	v_mul_f32_e32 v112, 0xbfb8aa3b, v104
	v_mul_f32_e32 v113, 0xbfb8aa3b, v105
	v_lshlrev_b32_e32 v110, 16, v201
	v_and_b32_e32 v111, 0xffff0000, v201
	v_mul_f32_e32 v118, 0xbfb8aa3b, v108
	v_mul_f32_e32 v119, 0xbfb8aa3b, v109
	v_exp_f32_e32 v112, v112
	v_exp_f32_e32 v113, v113
	v_mul_f32_e32 v114, 0xbfb8aa3b, v106
	v_mul_f32_e32 v115, 0xbfb8aa3b, v107
	v_mul_f32_e32 v120, 0xbfb8aa3b, v110
	v_mul_f32_e32 v121, 0xbfb8aa3b, v111
	v_exp_f32_e32 v118, v118
	v_exp_f32_e32 v119, v119
	v_exp_f32_e32 v114, v114
	v_exp_f32_e32 v115, v115
	v_exp_f32_e32 v120, v120
	v_exp_f32_e32 v121, v121
	v_add_f32_e32 v112, 1.0, v112
	v_add_f32_e32 v113, 1.0, v113
	v_add_f32_e32 v118, 1.0, v118
	v_add_f32_e32 v119, 1.0, v119
	v_rcp_f32_e32 v112, v112
	v_rcp_f32_e32 v113, v113
	v_add_f32_e32 v114, 1.0, v114
	v_add_f32_e32 v115, 1.0, v115
	v_add_f32_e32 v120, 1.0, v120
	v_add_f32_e32 v121, 1.0, v121
	v_rcp_f32_e32 v118, v118
	v_rcp_f32_e32 v119, v119
	v_rcp_f32_e32 v114, v114
	v_rcp_f32_e32 v115, v115
	v_rcp_f32_e32 v120, v120
	v_rcp_f32_e32 v121, v121
	v_pk_mul_f32 v[104:105], v[112:113], v[104:105]
	v_pk_mul_f32 v[108:109], v[118:119], v[108:109]
	v_pk_mul_f32 v[100:101], v[100:101], v[104:105]
	v_pk_mul_f32 v[106:107], v[114:115], v[106:107]
	v_pk_mul_f32 v[110:111], v[120:121], v[110:111]
	v_pk_mul_f32 v[104:105], v[96:97], v[108:109]
	v_cvt_pk_bf16_f32 v96, v100, v101
	v_lshlrev_b64 v[100:101], 11, v[116:117]
	v_pk_mul_f32 v[102:103], v[102:103], v[106:107]
	v_pk_mul_f32 v[106:107], v[98:99], v[110:111]
	v_lshl_add_u64 v[100:101], s[16:17], 0, v[100:101]
	v_cvt_pk_bf16_f32 v97, v102, v103
	v_cvt_pk_bf16_f32 v98, v104, v105
	v_cvt_pk_bf16_f32 v99, v106, v107
	v_lshl_add_u64 v[100:101], v[100:101], 0, v[144:145]
	global_store_dwordx4 v[100:101], v[96:99], off
	v_or_b32_e32 v100, 32, v146
	v_ashrrev_i32_e32 v101, 31, v100
	v_add_f32_e32 v102, 1.0, v84
	v_add_f32_e32 v103, 1.0, v85
	v_rcp_f32_e32 v84, v92
	v_rcp_f32_e32 v85, v93
	v_add_f32_e32 v104, 1.0, v86
	v_add_f32_e32 v105, 1.0, v87
	v_rcp_f32_e32 v86, v94
	v_rcp_f32_e32 v87, v95
	v_rcp_f32_e32 v92, v102
	v_rcp_f32_e32 v93, v103
	v_rcp_f32_e32 v94, v104
	v_rcp_f32_e32 v95, v105
	v_pk_mul_f32 v[84:85], v[88:89], v[84:85]
	v_pk_mul_f32 v[86:87], v[90:91], v[86:87]
	v_pk_mul_f32 v[80:81], v[80:81], v[92:93]
	v_pk_mul_f32 v[82:83], v[82:83], v[94:95]
	v_mul_f32_e32 v20, 0xbfb8aa3b, v20
	v_mul_f32_e32 v21, 0xbfb8aa3b, v21
	v_exp_f32_e32 v28, v28
	v_exp_f32_e32 v29, v29
	v_mul_f32_e32 v22, 0xbfb8aa3b, v22
	v_mul_f32_e32 v23, 0xbfb8aa3b, v23
	v_exp_f32_e32 v30, v30
	v_exp_f32_e32 v31, v31
	v_exp_f32_e32 v20, v20
	v_exp_f32_e32 v21, v21
	v_exp_f32_e32 v22, v22
	v_exp_f32_e32 v23, v23
	v_add_f32_e32 v28, 1.0, v28
	v_add_f32_e32 v29, 1.0, v29
	v_add_f32_e32 v30, 1.0, v30
	v_add_f32_e32 v31, 1.0, v31
	v_mul_f32_e32 v12, 0xbfb8aa3b, v12
	v_mul_f32_e32 v13, 0xbfb8aa3b, v13
	v_mul_f32_e32 v14, 0xbfb8aa3b, v14
	v_mul_f32_e32 v15, 0xbfb8aa3b, v15
	v_mul_f32_e32 v4, 0xbfb8aa3b, v4
	v_mul_f32_e32 v5, 0xbfb8aa3b, v5
	v_exp_f32_e32 v12, v12
	v_exp_f32_e32 v13, v13
	v_mul_f32_e32 v6, 0xbfb8aa3b, v6
	v_mul_f32_e32 v7, 0xbfb8aa3b, v7
	v_exp_f32_e32 v14, v14
	v_exp_f32_e32 v15, v15
	v_exp_f32_e32 v4, v4
	v_exp_f32_e32 v5, v5
	v_exp_f32_e32 v6, v6
	v_exp_f32_e32 v7, v7
	v_add_f32_e32 v12, 1.0, v12
	v_add_f32_e32 v13, 1.0, v13
	v_add_f32_e32 v14, 1.0, v14
	v_add_f32_e32 v15, 1.0, v15
	s_andn2_b64 vcc, exec, s[2:3]
	s_mov_b64 s[2:3], -1
	s_waitcnt vmcnt(7)
; __device__ __forceinline__ unsigned pk2(float lo, float hi) { f32x2 v = {lo, hi}; nbf2 r = __builtin_convertvector(v, nbf2); return __builtin_bit_cast(unsigned, r); }
; __device__ __forceinline__ float bf_lo(unsigned w) { return __uint_as_float(w << 16); }
; __device__ __forceinline__ float bf_hi(unsigned w) { return __uint_as_float(w & 0xffff0000u); }
; __device__ __forceinline__ float silu_f(float z) { return z * fast_rcp(1.0f + fast_exp2(-z * LOG2E)); }
; __device__ __forceinline__ float sigmoid_f(float z) { return fast_rcp(1.0f + fast_exp2(-z * LOG2E)); }
;     __device__ __forceinline__ void operator()(f32x4 (&acc)[2][2][4][2], const pg8::Unit& u, int wr, int wc, int fr, int fq, LAS unsigned char* lds) const {
;     ...
;                 const int r = u.pm * 256 + ai * 128 + wr * 64 + m * 16 + fr;
;                 const int oc = u.pn * 128 + wc * 32 + 8 * fq;
;                 const u32x4 zw = *(const u32x4*)(UZ + (size_t)r * NUZ + 1024 + oc);
;                 const f32x4 a0 = acc[ai][0][m][0], a1 = acc[ai][0][m][1], g0 = acc[ai][1][m][0], g1 = acc[ai][1][m][1];
;                 float o[8];
;                 o[0] = a0[0] * sigmoid_f(g0[0]) * silu_f(bf_lo(zw.x)); o[1] = a0[1] * sigmoid_f(g0[1]) * silu_f(bf_hi(zw.x));
;                 o[2] = a0[2] * sigmoid_f(g0[2]) * silu_f(bf_lo(zw.y)); o[3] = a0[3] * sigmoid_f(g0[3]) * silu_f(bf_hi(zw.y));
;                 o[4] = a1[0] * sigmoid_f(g1[0]) * silu_f(bf_lo(zw.z)); o[5] = a1[1] * sigmoid_f(g1[1]) * silu_f(bf_hi(zw.z));
;                 o[6] = a1[2] * sigmoid_f(g1[2]) * silu_f(bf_lo(zw.w)); o[7] = a1[3] * sigmoid_f(g1[3]) * silu_f(bf_hi(zw.w));
;                 u32x4 w; w.x = pk2(o[0], o[1]); w.y = pk2(o[2], o[3]); w.z = pk2(o[4], o[5]); w.w = pk2(o[6], o[7]);
;                 *(u32x4*)(O + (size_t)r * D + oc) = w;
	v_lshlrev_b32_e32 v88, 16, v202
	v_and_b32_e32 v89, 0xffff0000, v202
	v_lshlrev_b32_e32 v90, 16, v203
	v_and_b32_e32 v91, 0xffff0000, v203
	v_lshlrev_b32_e32 v92, 16, v204
	v_and_b32_e32 v93, 0xffff0000, v204
	v_mul_f32_e32 v96, 0xbfb8aa3b, v88
	v_mul_f32_e32 v97, 0xbfb8aa3b, v89
	v_lshlrev_b32_e32 v94, 16, v205
	v_and_b32_e32 v95, 0xffff0000, v205
	v_mul_f32_e32 v102, 0xbfb8aa3b, v92
	v_mul_f32_e32 v103, 0xbfb8aa3b, v93
	v_exp_f32_e32 v96, v96
	v_exp_f32_e32 v97, v97
	v_mul_f32_e32 v98, 0xbfb8aa3b, v90
	v_mul_f32_e32 v99, 0xbfb8aa3b, v91
	v_mul_f32_e32 v104, 0xbfb8aa3b, v94
	v_mul_f32_e32 v105, 0xbfb8aa3b, v95
	v_exp_f32_e32 v102, v102
	v_exp_f32_e32 v103, v103
	v_exp_f32_e32 v98, v98
	v_exp_f32_e32 v99, v99
	v_exp_f32_e32 v104, v104
	v_exp_f32_e32 v105, v105
	v_add_f32_e32 v96, 1.0, v96
	v_add_f32_e32 v97, 1.0, v97
	v_add_f32_e32 v102, 1.0, v102
	v_add_f32_e32 v103, 1.0, v103
	v_rcp_f32_e32 v96, v96
	v_rcp_f32_e32 v97, v97
	v_add_f32_e32 v98, 1.0, v98
	v_add_f32_e32 v99, 1.0, v99
	v_add_f32_e32 v104, 1.0, v104
	v_add_f32_e32 v105, 1.0, v105
	v_rcp_f32_e32 v102, v102
	v_rcp_f32_e32 v103, v103
	v_rcp_f32_e32 v98, v98
	v_rcp_f32_e32 v99, v99
	v_rcp_f32_e32 v104, v104
	v_rcp_f32_e32 v105, v105
	v_pk_mul_f32 v[88:89], v[96:97], v[88:89]
	v_pk_mul_f32 v[92:93], v[102:103], v[92:93]
	v_pk_mul_f32 v[84:85], v[84:85], v[88:89]
	v_pk_mul_f32 v[90:91], v[98:99], v[90:91]
	v_pk_mul_f32 v[94:95], v[104:105], v[94:95]
	v_pk_mul_f32 v[88:89], v[80:81], v[92:93]
	v_cvt_pk_bf16_f32 v80, v84, v85
	v_lshlrev_b64 v[84:85], 11, v[100:101]
	v_pk_mul_f32 v[86:87], v[86:87], v[90:91]
	v_pk_mul_f32 v[90:91], v[82:83], v[94:95]
	v_lshl_add_u64 v[84:85], s[16:17], 0, v[84:85]
	v_cvt_pk_bf16_f32 v81, v86, v87
	v_cvt_pk_bf16_f32 v82, v88, v89
	v_cvt_pk_bf16_f32 v83, v90, v91
	v_lshl_add_u64 v[84:85], v[84:85], 0, v[144:145]
	global_store_dwordx4 v[84:85], v[80:83], off
	v_or_b32_e32 v84, 48, v146
	v_ashrrev_i32_e32 v85, 31, v84
	v_add_f32_e32 v86, 1.0, v68
	v_add_f32_e32 v87, 1.0, v69
	v_rcp_f32_e32 v68, v76
	v_rcp_f32_e32 v69, v77
	v_rcp_f32_e32 v76, v86
	v_rcp_f32_e32 v77, v87
	v_add_f32_e32 v88, 1.0, v70
	v_add_f32_e32 v89, 1.0, v71
	v_rcp_f32_e32 v70, v78
	v_rcp_f32_e32 v71, v79
	v_pk_mul_f32 v[68:69], v[72:73], v[68:69]
	v_pk_mul_f32 v[64:65], v[64:65], v[76:77]
	v_rcp_f32_e32 v78, v88
	v_rcp_f32_e32 v79, v89
	v_pk_mul_f32 v[70:71], v[74:75], v[70:71]
	s_waitcnt vmcnt(7)
	v_lshlrev_b32_e32 v72, 16, v206
	v_and_b32_e32 v73, 0xffff0000, v206
	v_lshlrev_b32_e32 v76, 16, v208
	v_and_b32_e32 v77, 0xffff0000, v208
	v_lshlrev_b32_e32 v74, 16, v207
	v_and_b32_e32 v75, 0xffff0000, v207
	v_lshlrev_b32_e32 v80, 16, v209
	v_and_b32_e32 v81, 0xffff0000, v209
	v_mul_f32_e32 v82, 0xbfb8aa3b, v72
	v_mul_f32_e32 v83, 0xbfb8aa3b, v73
	v_mul_f32_e32 v88, 0xbfb8aa3b, v76
	v_mul_f32_e32 v89, 0xbfb8aa3b, v77
	v_mul_f32_e32 v86, 0xbfb8aa3b, v74
	v_mul_f32_e32 v87, 0xbfb8aa3b, v75
	v_mul_f32_e32 v90, 0xbfb8aa3b, v80
	v_mul_f32_e32 v91, 0xbfb8aa3b, v81
	v_exp_f32_e32 v82, v82
	v_exp_f32_e32 v83, v83
	v_exp_f32_e32 v88, v88
	v_exp_f32_e32 v89, v89
	v_exp_f32_e32 v86, v86
	v_exp_f32_e32 v87, v87
	v_exp_f32_e32 v90, v90
	v_exp_f32_e32 v91, v91
	v_add_f32_e32 v82, 1.0, v82
	v_add_f32_e32 v83, 1.0, v83
	v_add_f32_e32 v88, 1.0, v88
	v_add_f32_e32 v89, 1.0, v89
	v_add_f32_e32 v86, 1.0, v86
	v_add_f32_e32 v87, 1.0, v87
	v_add_f32_e32 v90, 1.0, v90
	v_add_f32_e32 v91, 1.0, v91
	v_rcp_f32_e32 v82, v82
	v_rcp_f32_e32 v83, v83
	v_rcp_f32_e32 v88, v88
	v_rcp_f32_e32 v89, v89
	v_rcp_f32_e32 v86, v86
	v_rcp_f32_e32 v87, v87
	v_rcp_f32_e32 v90, v90
	v_rcp_f32_e32 v91, v91
	v_pk_mul_f32 v[72:73], v[82:83], v[72:73]
	v_pk_mul_f32 v[76:77], v[88:89], v[76:77]
	v_pk_mul_f32 v[74:75], v[86:87], v[74:75]
	v_pk_mul_f32 v[68:69], v[68:69], v[72:73]
	v_pk_mul_f32 v[72:73], v[64:65], v[76:77]
	v_pk_mul_f32 v[64:65], v[66:67], v[78:79]
	v_pk_mul_f32 v[66:67], v[90:91], v[80:81]
	v_pk_mul_f32 v[70:71], v[70:71], v[74:75]
	v_pk_mul_f32 v[74:75], v[64:65], v[66:67]
	v_cvt_pk_bf16_f32 v64, v68, v69
	v_lshlrev_b64 v[68:69], 11, v[84:85]
	v_lshl_add_u64 v[68:69], s[16:17], 0, v[68:69]
	v_cvt_pk_bf16_f32 v65, v70, v71
	v_cvt_pk_bf16_f32 v66, v72, v73
	v_cvt_pk_bf16_f32 v67, v74, v75
	v_lshl_add_u64 v[68:69], v[68:69], 0, v[144:145]
	global_store_dwordx4 v[68:69], v[64:67], off
	v_add_u32_e32 v68, 0x80, v146
	v_ashrrev_i32_e32 v69, 31, v68
	v_add_f32_e32 v70, 1.0, v52
	v_add_f32_e32 v71, 1.0, v53
	v_rcp_f32_e32 v52, v60
	v_rcp_f32_e32 v53, v61
	v_add_f32_e32 v72, 1.0, v54
	v_add_f32_e32 v73, 1.0, v55
	v_rcp_f32_e32 v54, v62
	v_rcp_f32_e32 v55, v63
	v_rcp_f32_e32 v60, v70
	v_rcp_f32_e32 v61, v71
	v_pk_mul_f32 v[52:53], v[56:57], v[52:53]
	v_pk_mul_f32 v[54:55], v[58:59], v[54:55]
	v_rcp_f32_e32 v62, v72
	v_pk_mul_f32 v[48:49], v[48:49], v[60:61]
	v_rcp_f32_e32 v63, v73
	s_waitcnt vmcnt(7)
; __device__ __forceinline__ unsigned pk2(float lo, float hi) { f32x2 v = {lo, hi}; nbf2 r = __builtin_convertvector(v, nbf2); return __builtin_bit_cast(unsigned, r); }
; __device__ __forceinline__ float bf_lo(unsigned w) { return __uint_as_float(w << 16); }
; __device__ __forceinline__ float bf_hi(unsigned w) { return __uint_as_float(w & 0xffff0000u); }
; __device__ __forceinline__ float silu_f(float z) { return z * fast_rcp(1.0f + fast_exp2(-z * LOG2E)); }
; __device__ __forceinline__ float sigmoid_f(float z) { return fast_rcp(1.0f + fast_exp2(-z * LOG2E)); }
;     __device__ __forceinline__ void operator()(f32x4 (&acc)[2][2][4][2], const pg8::Unit& u, int wr, int wc, int fr, int fq, LAS unsigned char* lds) const {
;     ...
;                 const int r = u.pm * 256 + ai * 128 + wr * 64 + m * 16 + fr;
;                 const int oc = u.pn * 128 + wc * 32 + 8 * fq;
;                 const u32x4 zw = *(const u32x4*)(UZ + (size_t)r * NUZ + 1024 + oc);
;                 const f32x4 a0 = acc[ai][0][m][0], a1 = acc[ai][0][m][1], g0 = acc[ai][1][m][0], g1 = acc[ai][1][m][1];
;                 float o[8];
;                 o[0] = a0[0] * sigmoid_f(g0[0]) * silu_f(bf_lo(zw.x)); o[1] = a0[1] * sigmoid_f(g0[1]) * silu_f(bf_hi(zw.x));
;                 o[2] = a0[2] * sigmoid_f(g0[2]) * silu_f(bf_lo(zw.y)); o[3] = a0[3] * sigmoid_f(g0[3]) * silu_f(bf_hi(zw.y));
;                 o[4] = a1[0] * sigmoid_f(g1[0]) * silu_f(bf_lo(zw.z)); o[5] = a1[1] * sigmoid_f(g1[1]) * silu_f(bf_hi(zw.z));
;                 o[6] = a1[2] * sigmoid_f(g1[2]) * silu_f(bf_lo(zw.w)); o[7] = a1[3] * sigmoid_f(g1[3]) * silu_f(bf_hi(zw.w));
;                 u32x4 w; w.x = pk2(o[0], o[1]); w.y = pk2(o[2], o[3]); w.z = pk2(o[4], o[5]); w.w = pk2(o[6], o[7]);
;                 *(u32x4*)(O + (size_t)r * D + oc) = w;
	v_lshlrev_b32_e32 v56, 16, v210
	v_and_b32_e32 v57, 0xffff0000, v210
	v_lshlrev_b32_e32 v58, 16, v211
	v_and_b32_e32 v59, 0xffff0000, v211
	v_lshlrev_b32_e32 v60, 16, v212
	v_and_b32_e32 v61, 0xffff0000, v212
	v_lshlrev_b32_e32 v64, 16, v213
	v_and_b32_e32 v65, 0xffff0000, v213
	v_mul_f32_e32 v66, 0xbfb8aa3b, v56
	v_mul_f32_e32 v67, 0xbfb8aa3b, v57
	v_exp_f32_e32 v66, v66
	v_exp_f32_e32 v67, v67
	v_mul_f32_e32 v72, 0xbfb8aa3b, v60
	v_mul_f32_e32 v73, 0xbfb8aa3b, v61
	v_add_f32_e32 v66, 1.0, v66
	v_add_f32_e32 v67, 1.0, v67
	v_mul_f32_e32 v70, 0xbfb8aa3b, v58
	v_mul_f32_e32 v71, 0xbfb8aa3b, v59
	v_mul_f32_e32 v74, 0xbfb8aa3b, v64
	v_mul_f32_e32 v75, 0xbfb8aa3b, v65
	v_exp_f32_e32 v72, v72
	v_exp_f32_e32 v73, v73
	v_rcp_f32_e32 v66, v66
	v_rcp_f32_e32 v67, v67
	v_exp_f32_e32 v70, v70
	v_exp_f32_e32 v71, v71
	v_exp_f32_e32 v74, v74
	v_exp_f32_e32 v75, v75
	v_add_f32_e32 v72, 1.0, v72
	v_add_f32_e32 v73, 1.0, v73
	v_pk_mul_f32 v[56:57], v[66:67], v[56:57]
	v_add_f32_e32 v70, 1.0, v70
	v_add_f32_e32 v71, 1.0, v71
	v_add_f32_e32 v74, 1.0, v74
	v_rcp_f32_e32 v72, v72
	v_rcp_f32_e32 v73, v73
	v_pk_mul_f32 v[52:53], v[52:53], v[56:57]
	v_add_f32_e32 v56, 1.0, v75
	v_rcp_f32_e32 v70, v70
	v_rcp_f32_e32 v71, v71
	v_rcp_f32_e32 v74, v74
	v_rcp_f32_e32 v75, v56
	v_pk_mul_f32 v[56:57], v[72:73], v[60:61]
	v_pk_mul_f32 v[58:59], v[70:71], v[58:59]
	v_pk_mul_f32 v[56:57], v[48:49], v[56:57]
	v_pk_mul_f32 v[48:49], v[50:51], v[62:63]
	v_pk_mul_f32 v[50:51], v[74:75], v[64:65]
	v_pk_mul_f32 v[54:55], v[54:55], v[58:59]
	v_pk_mul_f32 v[58:59], v[48:49], v[50:51]
	v_cvt_pk_bf16_f32 v48, v52, v53
	v_lshlrev_b64 v[52:53], 11, v[68:69]
	v_lshl_add_u64 v[52:53], s[16:17], 0, v[52:53]
	v_cvt_pk_bf16_f32 v49, v54, v55
	v_cvt_pk_bf16_f32 v50, v56, v57
	v_cvt_pk_bf16_f32 v51, v58, v59
	v_lshl_add_u64 v[52:53], v[52:53], 0, v[144:145]
	global_store_dwordx4 v[52:53], v[48:51], off
	v_add_u32_e32 v52, 0x90, v146
	v_ashrrev_i32_e32 v53, 31, v52
	v_add_f32_e32 v54, 1.0, v36
	v_add_f32_e32 v55, 1.0, v37
	v_rcp_f32_e32 v36, v44
	v_rcp_f32_e32 v37, v45
	v_add_f32_e32 v56, 1.0, v38
	v_add_f32_e32 v58, 1.0, v39
	v_rcp_f32_e32 v38, v46
	v_rcp_f32_e32 v39, v47
	v_rcp_f32_e32 v44, v54
	v_rcp_f32_e32 v45, v55
	v_pk_mul_f32 v[36:37], v[40:41], v[36:37]
	v_pk_mul_f32 v[38:39], v[42:43], v[38:39]
	v_rcp_f32_e32 v46, v56
	v_pk_mul_f32 v[32:33], v[32:33], v[44:45]
	s_waitcnt vmcnt(7)
	v_lshlrev_b32_e32 v40, 16, v214
	v_and_b32_e32 v41, 0xffff0000, v214
	v_lshlrev_b32_e32 v42, 16, v215
	v_lshlrev_b32_e32 v44, 16, v216
	v_and_b32_e32 v45, 0xffff0000, v216
	v_mul_f32_e32 v47, 0xbfb8aa3b, v40
	v_mul_f32_e32 v50, 0xbfb8aa3b, v41
	v_and_b32_e32 v43, 0xffff0000, v215
	v_lshlrev_b32_e32 v48, 16, v217
	v_and_b32_e32 v49, 0xffff0000, v217
	v_mul_f32_e32 v51, 0xbfb8aa3b, v42
	v_exp_f32_e32 v47, v47
	v_exp_f32_e32 v50, v50
	v_exp_f32_e32 v51, v51
	v_mul_f32_e32 v54, 0xbfb8aa3b, v43
	v_mul_f32_e32 v57, 0xbfb8aa3b, v48
	v_mul_f32_e32 v55, 0xbfb8aa3b, v44
	v_mul_f32_e32 v56, 0xbfb8aa3b, v45
	v_exp_f32_e32 v54, v54
	v_exp_f32_e32 v60, v57
	v_add_f32_e32 v47, 1.0, v47
	v_add_f32_e32 v57, 1.0, v50
	v_mul_f32_e32 v59, 0xbfb8aa3b, v49
	v_exp_f32_e32 v55, v55
	v_exp_f32_e32 v56, v56
	v_add_f32_e32 v61, 1.0, v51
	v_rcp_f32_e32 v50, v47
	v_rcp_f32_e32 v51, v57
	v_exp_f32_e32 v59, v59
	v_add_f32_e32 v62, 1.0, v54
	v_add_f32_e32 v63, 1.0, v55
	v_add_f32_e32 v64, 1.0, v56
	v_rcp_f32_e32 v54, v61
	v_rcp_f32_e32 v55, v62
	v_pk_mul_f32 v[40:41], v[50:51], v[40:41]
	v_rcp_f32_e32 v56, v63
	v_rcp_f32_e32 v57, v64
	v_pk_mul_f32 v[36:37], v[36:37], v[40:41]
	v_add_f32_e32 v40, 1.0, v60
	v_add_f32_e32 v41, 1.0, v59
	v_rcp_f32_e32 v47, v58
	v_rcp_f32_e32 v40, v40
	v_rcp_f32_e32 v41, v41
	v_pk_mul_f32 v[42:43], v[54:55], v[42:43]
	s_nop 0
	v_pk_mul_f32 v[38:39], v[38:39], v[42:43]
	v_pk_mul_f32 v[42:43], v[56:57], v[44:45]
	s_nop 0
	v_pk_mul_f32 v[42:43], v[32:33], v[42:43]
	v_pk_mul_f32 v[32:33], v[34:35], v[46:47]
	v_pk_mul_f32 v[34:35], v[40:41], v[48:49]
	s_nop 0
	v_pk_mul_f32 v[40:41], v[32:33], v[34:35]
	v_cvt_pk_bf16_f32 v32, v36, v37
	v_lshlrev_b64 v[36:37], 11, v[52:53]
	v_lshl_add_u64 v[36:37], s[16:17], 0, v[36:37]
	v_cvt_pk_bf16_f32 v33, v38, v39
	v_cvt_pk_bf16_f32 v34, v42, v43
	v_cvt_pk_bf16_f32 v35, v40, v41
	v_lshl_add_u64 v[36:37], v[36:37], 0, v[144:145]
	global_store_dwordx4 v[36:37], v[32:35], off
	v_add_u32_e32 v36, 0xa0, v146
	v_ashrrev_i32_e32 v37, 31, v36
	v_add_f32_e32 v38, 1.0, v20
	v_add_f32_e32 v39, 1.0, v21
	v_rcp_f32_e32 v20, v28
	v_rcp_f32_e32 v21, v29
	v_add_f32_e32 v40, 1.0, v22
	v_add_f32_e32 v42, 1.0, v23
	v_rcp_f32_e32 v22, v30
	v_rcp_f32_e32 v23, v31
	v_rcp_f32_e32 v28, v38
	v_rcp_f32_e32 v29, v39
	v_pk_mul_f32 v[20:21], v[24:25], v[20:21]
	v_pk_mul_f32 v[22:23], v[26:27], v[22:23]
	v_rcp_f32_e32 v30, v40
	v_pk_mul_f32 v[16:17], v[16:17], v[28:29]
	s_waitcnt vmcnt(7)
; __device__ __forceinline__ unsigned pk2(float lo, float hi) { f32x2 v = {lo, hi}; nbf2 r = __builtin_convertvector(v, nbf2); return __builtin_bit_cast(unsigned, r); }
; __device__ __forceinline__ float bf_lo(unsigned w) { return __uint_as_float(w << 16); }
; __device__ __forceinline__ float bf_hi(unsigned w) { return __uint_as_float(w & 0xffff0000u); }
; __device__ __forceinline__ float silu_f(float z) { return z * fast_rcp(1.0f + fast_exp2(-z * LOG2E)); }
; __device__ __forceinline__ float sigmoid_f(float z) { return fast_rcp(1.0f + fast_exp2(-z * LOG2E)); }
; #define PG8_BAR __builtin_amdgcn_s_barrier()
; template <class Epi, class Sched>
; __device__ __forceinline__ void gemm_phase(LAS unsigned char* lds, const Gemm g, const Sched& S, const Epi& E) {
;     ...
;         if (!has_next) break;
; #pragma unroll
;         for (int a = 0; a < 2; ++a)
; #pragma unroll
;             for (int b = 0; b < 2; ++b)
; #pragma unroll
;                 for (int m = 0; m < 4; ++m)
; #pragma unroll
;                     for (int n = 0; n < 2; ++n) acc[a][b][m][n] = (f32x4){0.f, 0.f, 0.f, 0.f};
;         cur = nxt; cA = nA; cB = nB; ++ui;
;         if (wr == 1) PG8_BAR;
;     __device__ __forceinline__ void operator()(f32x4 (&acc)[2][2][4][2], const pg8::Unit& u, int wr, int wc, int fr, int fq, LAS unsigned char* lds) const {
;     ...
;                 const int r = u.pm * 256 + ai * 128 + wr * 64 + m * 16 + fr;
;                 const int oc = u.pn * 128 + wc * 32 + 8 * fq;
;                 const u32x4 zw = *(const u32x4*)(UZ + (size_t)r * NUZ + 1024 + oc);
;                 const f32x4 a0 = acc[ai][0][m][0], a1 = acc[ai][0][m][1], g0 = acc[ai][1][m][0], g1 = acc[ai][1][m][1];
;                 float o[8];
;                 o[0] = a0[0] * sigmoid_f(g0[0]) * silu_f(bf_lo(zw.x)); o[1] = a0[1] * sigmoid_f(g0[1]) * silu_f(bf_hi(zw.x));
;                 o[2] = a0[2] * sigmoid_f(g0[2]) * silu_f(bf_lo(zw.y)); o[3] = a0[3] * sigmoid_f(g0[3]) * silu_f(bf_hi(zw.y));
;                 o[4] = a1[0] * sigmoid_f(g1[0]) * silu_f(bf_lo(zw.z)); o[5] = a1[1] * sigmoid_f(g1[1]) * silu_f(bf_hi(zw.z));
;                 o[6] = a1[2] * sigmoid_f(g1[2]) * silu_f(bf_lo(zw.w)); o[7] = a1[3] * sigmoid_f(g1[3]) * silu_f(bf_hi(zw.w));
;                 u32x4 w; w.x = pk2(o[0], o[1]); w.y = pk2(o[2], o[3]); w.z = pk2(o[4], o[5]); w.w = pk2(o[6], o[7]);
;                 *(u32x4*)(O + (size_t)r * D + oc) = w;
	v_lshlrev_b32_e32 v24, 16, v218
	v_and_b32_e32 v25, 0xffff0000, v218
	v_lshlrev_b32_e32 v26, 16, v219
	v_lshlrev_b32_e32 v28, 16, v220
	v_and_b32_e32 v29, 0xffff0000, v220
	v_mul_f32_e32 v31, 0xbfb8aa3b, v24
	v_mul_f32_e32 v34, 0xbfb8aa3b, v25
	v_and_b32_e32 v27, 0xffff0000, v219
	v_lshlrev_b32_e32 v32, 16, v221
	v_and_b32_e32 v33, 0xffff0000, v221
	v_mul_f32_e32 v35, 0xbfb8aa3b, v26
	v_exp_f32_e32 v31, v31
	v_exp_f32_e32 v34, v34
	v_exp_f32_e32 v35, v35
	v_mul_f32_e32 v38, 0xbfb8aa3b, v27
	v_add_f32_e32 v31, 1.0, v31
	v_add_f32_e32 v41, 1.0, v34
	v_add_f32_e32 v44, 1.0, v35
	v_rcp_f32_e32 v34, v31
	v_rcp_f32_e32 v35, v41
	v_mul_f32_e32 v39, 0xbfb8aa3b, v28
	v_mul_f32_e32 v40, 0xbfb8aa3b, v29
	v_exp_f32_e32 v38, v38
	v_pk_mul_f32 v[24:25], v[34:35], v[24:25]
	v_mul_f32_e32 v43, 0xbfb8aa3b, v32
	v_exp_f32_e32 v39, v39
	v_exp_f32_e32 v40, v40
	v_pk_mul_f32 v[20:21], v[20:21], v[24:25]
	v_mul_f32_e32 v25, 0xbfb8aa3b, v33
	v_exp_f32_e32 v24, v43
	v_exp_f32_e32 v25, v25
	v_add_f32_e32 v45, 1.0, v38
	v_add_f32_e32 v46, 1.0, v39
	v_add_f32_e32 v47, 1.0, v40
	v_rcp_f32_e32 v38, v44
	v_rcp_f32_e32 v39, v45
	v_rcp_f32_e32 v40, v46
	v_rcp_f32_e32 v41, v47
	v_add_f32_e32 v24, 1.0, v24
	v_add_f32_e32 v25, 1.0, v25
	v_rcp_f32_e32 v31, v42
	v_rcp_f32_e32 v24, v24
	v_rcp_f32_e32 v25, v25
	v_pk_mul_f32 v[26:27], v[38:39], v[26:27]
	s_nop 0
	v_pk_mul_f32 v[22:23], v[22:23], v[26:27]
	v_pk_mul_f32 v[26:27], v[40:41], v[28:29]
	s_nop 0
	v_pk_mul_f32 v[26:27], v[16:17], v[26:27]
	v_pk_mul_f32 v[16:17], v[18:19], v[30:31]
	v_pk_mul_f32 v[18:19], v[24:25], v[32:33]
	s_nop 0
	v_pk_mul_f32 v[24:25], v[16:17], v[18:19]
	v_cvt_pk_bf16_f32 v16, v20, v21
	v_lshlrev_b64 v[20:21], 11, v[36:37]
	v_lshl_add_u64 v[20:21], s[16:17], 0, v[20:21]
	v_cvt_pk_bf16_f32 v17, v22, v23
	v_cvt_pk_bf16_f32 v18, v26, v27
	v_cvt_pk_bf16_f32 v19, v24, v25
	v_lshl_add_u64 v[20:21], v[20:21], 0, v[144:145]
	global_store_dwordx4 v[20:21], v[16:19], off
	v_add_u32_e32 v20, 0xb0, v146
	v_ashrrev_i32_e32 v21, 31, v20
	v_add_f32_e32 v22, 1.0, v4
	v_add_f32_e32 v23, 1.0, v5
	v_rcp_f32_e32 v4, v12
	v_rcp_f32_e32 v5, v13
	v_add_f32_e32 v24, 1.0, v6
	v_add_f32_e32 v26, 1.0, v7
	v_rcp_f32_e32 v6, v14
	v_rcp_f32_e32 v7, v15
	v_rcp_f32_e32 v12, v22
	v_rcp_f32_e32 v13, v23
	v_pk_mul_f32 v[4:5], v[8:9], v[4:5]
	v_pk_mul_f32 v[6:7], v[10:11], v[6:7]
	v_rcp_f32_e32 v14, v24
	v_pk_mul_f32 v[0:1], v[0:1], v[12:13]
	s_waitcnt vmcnt(7)
	v_lshlrev_b32_e32 v8, 16, v222
	v_and_b32_e32 v9, 0xffff0000, v222
	v_lshlrev_b32_e32 v10, 16, v223
	v_and_b32_e32 v11, 0xffff0000, v223
	v_mul_f32_e32 v15, 0xbfb8aa3b, v8
	v_mul_f32_e32 v16, 0xbfb8aa3b, v9
	v_lshlrev_b32_e32 v12, 16, v224
	v_and_b32_e32 v13, 0xffff0000, v224
	v_mul_f32_e32 v17, 0xbfb8aa3b, v10
	v_mul_f32_e32 v18, 0xbfb8aa3b, v11
	v_exp_f32_e32 v15, v15
	v_exp_f32_e32 v16, v16
	v_mul_f32_e32 v22, 0xbfb8aa3b, v12
	v_mul_f32_e32 v23, 0xbfb8aa3b, v13
	v_exp_f32_e32 v17, v17
	v_exp_f32_e32 v18, v18
	v_exp_f32_e32 v22, v22
	v_exp_f32_e32 v23, v23
	v_add_f32_e32 v15, 1.0, v15
	v_add_f32_e32 v24, 1.0, v16
	v_add_f32_e32 v25, 1.0, v17
	v_add_f32_e32 v18, 1.0, v18
	v_rcp_f32_e32 v16, v15
	v_rcp_f32_e32 v17, v24
	v_add_f32_e32 v27, 1.0, v22
	v_add_f32_e32 v28, 1.0, v23
	v_rcp_f32_e32 v22, v25
	v_rcp_f32_e32 v23, v18
	v_pk_mul_f32 v[8:9], v[16:17], v[8:9]
	v_rcp_f32_e32 v24, v27
	v_pk_mul_f32 v[4:5], v[4:5], v[8:9]
	v_pk_mul_f32 v[10:11], v[22:23], v[10:11]
	v_lshlrev_b32_e32 v8, 16, v225
	v_and_b32_e32 v9, 0xffff0000, v225
	v_pk_mul_f32 v[6:7], v[6:7], v[10:11]
	v_mul_f32_e32 v10, 0xbfb8aa3b, v8
	v_mul_f32_e32 v11, 0xbfb8aa3b, v9
	v_exp_f32_e32 v10, v10
	v_exp_f32_e32 v11, v11
	v_rcp_f32_e32 v25, v28
	v_rcp_f32_e32 v15, v26
	v_add_f32_e32 v10, 1.0, v10
	v_add_f32_e32 v11, 1.0, v11
	v_rcp_f32_e32 v10, v10
	v_rcp_f32_e32 v11, v11
	v_pk_mul_f32 v[12:13], v[24:25], v[12:13]
	s_nop 0
	v_pk_mul_f32 v[12:13], v[0:1], v[12:13]
	v_pk_mul_f32 v[0:1], v[2:3], v[14:15]
	v_pk_mul_f32 v[2:3], v[10:11], v[8:9]
	s_nop 0
	v_pk_mul_f32 v[8:9], v[0:1], v[2:3]
	v_cvt_pk_bf16_f32 v0, v4, v5
	v_lshlrev_b64 v[4:5], 11, v[20:21]
	v_lshl_add_u64 v[4:5], s[16:17], 0, v[4:5]
	v_cvt_pk_bf16_f32 v1, v6, v7
	v_cvt_pk_bf16_f32 v2, v12, v13
	v_cvt_pk_bf16_f32 v3, v8, v9
	v_lshl_add_u64 v[4:5], v[4:5], 0, v[144:145]
	global_store_dwordx4 v[4:5], v[0:3], off
	s_cbranch_vccnz .LBB0_826
	s_andn2_b64 vcc, exec, s[4:5]
	s_cbranch_vccnz .LBB0_825
	s_barrier
	s_branch .LBB0_825
